# one-time census poll of the grid barrier issues its 16 counter loads together
# baseline (speedup 1.0000x reference)
.LBB0_669:
	s_mov_b64 s[4:5], -1
	s_waitcnt lgkmcnt(0)
	v_readlane_b32 s0, v253, 7
	v_readlane_b32 s1, v253, 8
	s_nop 4
	global_load_dword v0, v113, s[0:1] sc1
	v_readlane_b32 s0, v253, 9
	v_readlane_b32 s1, v253, 10
	s_nop 4
	global_load_dword v1, v113, s[0:1] sc1
	v_readlane_b32 s0, v253, 11
	v_readlane_b32 s1, v253, 12
	s_nop 4
	global_load_dword v2, v113, s[0:1] sc1
	v_readlane_b32 s0, v253, 13
	v_readlane_b32 s1, v253, 14
	s_nop 4
	global_load_dword v3, v113, s[0:1] sc1
	v_readlane_b32 s0, v253, 15
	v_readlane_b32 s1, v253, 16
	s_nop 4
	global_load_dword v4, v113, s[0:1] sc1
	v_readlane_b32 s0, v253, 17
	v_readlane_b32 s1, v253, 18
	s_nop 4
	global_load_dword v5, v113, s[0:1] sc1
	v_readlane_b32 s0, v253, 19
	v_readlane_b32 s1, v253, 20
	s_nop 4
	global_load_dword v6, v113, s[0:1] sc1
	v_readlane_b32 s0, v253, 21
	v_readlane_b32 s1, v253, 22
	s_nop 4
	global_load_dword v7, v113, s[0:1] sc1
	v_readlane_b32 s0, v253, 23
	v_readlane_b32 s1, v253, 24
	s_nop 4
	global_load_dword v8, v113, s[0:1] sc1
	v_readlane_b32 s0, v253, 25
	v_readlane_b32 s1, v253, 26
	s_nop 4
	global_load_dword v9, v113, s[0:1] sc1
	v_readlane_b32 s0, v253, 27
	v_readlane_b32 s1, v253, 28
	s_nop 4
	global_load_dword v10, v113, s[0:1] sc1
	v_readlane_b32 s0, v253, 29
	v_readlane_b32 s1, v253, 30
	s_nop 4
	global_load_dword v11, v113, s[0:1] sc1
	v_readlane_b32 s0, v253, 31
	v_readlane_b32 s1, v253, 32
	s_nop 4
	global_load_dword v12, v113, s[0:1] sc1
	v_readlane_b32 s0, v253, 33
	v_readlane_b32 s1, v253, 34
	s_nop 4
	global_load_dword v13, v113, s[0:1] sc1
	v_readlane_b32 s0, v253, 35
	v_readlane_b32 s1, v253, 36
	s_nop 4
	global_load_dword v14, v113, s[0:1] sc1
	v_readlane_b32 s0, v253, 37
	v_readlane_b32 s1, v253, 38
	s_nop 4
	global_load_dword v15, v113, s[0:1] sc1
	s_mov_b64 s[0:1], -1
	s_waitcnt vmcnt(0)
	v_add_u32_e32 v16, v1, v0
	v_add_u32_e32 v16, v16, v2
	v_add_u32_e32 v16, v16, v3
	v_add_u32_e32 v16, v16, v4
	v_add_u32_e32 v16, v16, v5
	v_add_u32_e32 v16, v16, v6
	v_add_u32_e32 v16, v16, v7
	v_add_u32_e32 v16, v16, v8
	v_add_u32_e32 v16, v16, v9
	v_add_u32_e32 v16, v16, v10
	v_add_u32_e32 v16, v16, v11
	v_add_u32_e32 v16, v16, v12
	v_add_u32_e32 v16, v16, v13
	v_add_u32_e32 v16, v16, v14
	v_add_u32_e32 v16, v16, v15
	v_cmp_eq_u32_e32 vcc, s19, v16
	s_cbranch_vccnz .LBB0_668
	s_and_b32 s0, s9, 0xff
	s_cmp_eq_u32 s0, 0
	s_mov_b64 s[0:1], -1
	s_mov_b64 s[6:7], -1
	s_sleep 1
	s_cbranch_scc1 .LBB0_673
	s_and_b64 vcc, exec, s[6:7]
	s_cbranch_vccz .LBB0_668
